# POST phase (7) unit order: each XCD takes 32 consecutive units (A tile fetched once per XCD instead of by six XCDs)
# baseline (speedup 1.0000x reference)
; #define PH(n, sync_) if (plo <= (n) && (n) <= phi) { if ((n) > plo && (sync_)) { if ((n) == 1) { grid.sync(); xb = xcd_barrier_post((unsigned*)(ws + O_XBAR), (volatile LAS unsigned*)&xb_words); } else xcd_barrier(xb); }
; template <int EPI>
; __device__ __forceinline__ void gemm_phase(const Params& p, const u16* __restrict__ A, int lda, const u16* __restrict__ BT, int ldb,
;                            int K, int N, u16* __restrict__ outb, int ldo, int resid_in, int boff) {
;     ...
;   const int NT = N / 128;
;   const int tiles = (MT / 256) * NT;
;   const int KTALL = K / 64;
;   float* part = (float*)(p.ws + O_PART);
;   int bstart = (int)blockIdx.x - boff;
;   if (bstart < 0) bstart += gridDim.x;
;   const size_t a64 = (size_t)64 * lda, b64 = (size_t)64 * ldb;
;   const int G = gridDim.x;
;   int t_full = tiles, split = 1;
;   if (EPI == EPI_RES) {
;     const int tail = tiles % G;
;     if (tail > 0 && (G % tail) == 0 && (KTALL % (G / tail)) == 0) { t_full = tiles - tail; const int smax = (KTALL >= 64) ? 8 : 4; split = (G / tail) > smax ? smax : (G / tail); }
;   }
;   const int units = t_full + (tiles - t_full) * split;
; __global__ void __launch_bounds__(512) mega(Params p, int plo, int phi) {
;     ...
;   PH(7, 1) gemm_phase<EPI_POST>(p, WSB(O_LIN + 256), 256, WSB(O_WLG), 128, 128, 768, nullptr, 0, 0, 0); PHEND
.Lgm_par7:
	s_add_u32 s16, s96, 0xcbc8200
	s_addc_u32 s17, s97, 0
	s_add_u32 s20, s96, 0x2db0000
	s_addc_u32 s21, s97, 0
	s_add_u32 s22, s96, 0x5008100
	s_addc_u32 s23, s97, 0
	s_movk_i32 s24, 0x800
	s_mov_b32 s25, 6
	s_mov_b32 s26, 0x2aaaaaab
	s_mov_b32 s27, 4
	s_movk_i32 s28, 0x18c
	s_movk_i32 s29, 0x100
	s_mov_b32 s30, 5
	s_movk_i32 s38, 0x18c
	s_mov_b32 s39, 2
	s_mov_b32 s44, 0
	s_mov_b32 s45, 9
	s_mov_b32 s46, 8
	s_branch .Lgm_common

; template <int EPI>
; __device__ __forceinline__ void gemm_phase(const Params& p, const u16* __restrict__ A, int lda, const u16* __restrict__ BT, int ldb,
;                            int K, int N, u16* __restrict__ outb, int ldo, int resid_in, int boff) {
;     ...
;   for (int un = bstart; un < units; un += G) {
;     int tl = un, kbeg = 0, KT = KTALL;
;     bool part_unit = false;
;     if (un >= t_full) { const int v = un - t_full; tl = t_full + v / split; KT = KTALL / split; kbeg = (v % split) * KT; part_unit = true; }
;     int mt = tl / NT, nt = tl % NT;
;     if (EPI == EPI_RES && NT == 8 && G == 256 && !part_unit) {
;       const int rr = tl >> 8, bb = tl & 255;
;       const int xx = bb & 7, jj = bb >> 3;
;       mt = rr * 32 + xx * 4 + (jj >> 3);
;       nt = jj & 7;
;     } else if ((EPI == EPI_FF1 || EPI == EPI_SCALE) && G == 256 && (NT == 32 || NT == 16) && tl < (tiles & ~255)) {
;       const int rr = tl >> 8, bb = tl & 255;
;       const int xx = bb & 7, jj = bb >> 3;
;       if (NT == 32) { mt = rr * 8 + (xx >> 2) * 4 + (jj >> 3); nt = (xx & 3) * 8 + (jj & 7); }
;       else { mt = rr * 16 + (xx >> 1) * 4 + (jj >> 3); nt = (xx & 1) * 8 + (jj & 7); }
;     }
.Lgm_nopanel_c:
	s_cmp_lg_u32 s30, 5
	s_cbranch_scc1 .Lgm_plain2_c
	s_mov_b32 s37, s36
	s_cmp_lt_u32 s37, 244
	s_cbranch_scc1 .Lgm_plain2_c
	s_add_u32 s36, s37, 140
	s_cmp_lt_u32 s37, 256
	s_cbranch_scc1 .Lgm_plain2_c
	s_mov_b32 s36, s37
	s_cmp_lt_u32 s37, 384
	s_cbranch_scc1 .Lgm_plain2_c
	s_sub_u32 s36, s37, 140
